# static wave priority in the diff phase removed (no longer pays after the exp deferral restructure)
# baseline (speedup 1.0000x reference)
; __device__ __forceinline__ int lane_now() { int l; asm volatile("v_mbcnt_lo_u32_b32 %0, -1, 0\n\tv_mbcnt_hi_u32_b32 %0, -1, %0" : "=v"(l)); return l; }
; __global__ void __launch_bounds__(NWAVES * 64, 2) hybrid_fwd(Args args) {
;     ...
;     if (IN(4)) {
;         const int lane4 = lane_now(); const int tid4 = wid * 64 + lane4;
;         float lam;
;         { const float p1 = args.in[9][lane4] * args.in[10][lane4], p2 = args.in[11][lane4] * args.in[12][lane4];
;           lam = expf(wave_sum(p1)) - expf(wave_sum(p2)) + 0.2f; }
;         bool fixm;
;         { float gq = fabsf(args.in[7][lane4]), gk = fabsf(args.in[8][lane4]);
; #pragma unroll
;           for (int o2 = 1; o2 < 64; o2 <<= 1) { gq = fmaxf(gq, __shfl_xor(gq, o2)); gk = fmaxf(gk, __shfl_xor(gk, o2)); }
;           fixm = (8.f * gq * gk * LOG2E <= 100.f); }
.LBB0_372:
	s_cmp_lt_i32 s92, 5
	s_cselect_b64 s[2:3], -1, 0
	s_and_b64 s[0:1], s[2:3], s[0:1]
	v_writelane_b32 v252, s0, 53
	s_andn2_b64 vcc, exec, s[0:1]
	s_nop 0
	v_writelane_b32 v252, s1, 54
	v_writelane_b32 v252, s74, 55
	v_writelane_b32 v252, s86, 56
	s_nop 1
	v_writelane_b32 v252, s87, 57
	s_cbranch_vccnz .LBB0_464
	v_writelane_b32 v252, s80, 58
	v_mbcnt_lo_u32_b32 v0, -1, 0
	v_mbcnt_hi_u32_b32 v0, -1, v0
	v_writelane_b32 v251, s88, 0
	v_ashrrev_i32_e32 v1, 31, v0
	v_writelane_b32 v252, s81, 59
	v_writelane_b32 v252, s78, 60
	v_lshlrev_b64 v[0:1], 2, v[0:1]
	v_writelane_b32 v251, s89, 1
	v_writelane_b32 v252, s79, 61
	v_writelane_b32 v252, s90, 62
	v_writelane_b32 v251, s68, 2
	s_cmpk_lt_i32 s72, 0x100
	v_writelane_b32 v252, s91, 63
	v_writelane_b32 v251, s69, 3
	v_readlane_b32 s16, v252, 37
	v_readlane_b32 s18, v252, 39
	v_readlane_b32 s19, v252, 40
	v_readlane_b32 s20, v252, 41
	v_readlane_b32 s21, v252, 42
	v_lshl_add_u64 v[2:3], s[18:19], 0, v[0:1]
	v_readlane_b32 s22, v252, 43
	v_readlane_b32 s23, v252, 44
	global_load_dword v4, v[2:3], off
	v_lshl_add_u64 v[2:3], s[20:21], 0, v[0:1]
	v_readlane_b32 s24, v252, 45
	v_readlane_b32 s25, v252, 46
	global_load_dword v5, v[2:3], off
	v_lshl_add_u64 v[2:3], s[22:23], 0, v[0:1]
	v_readlane_b32 s0, v252, 18
	v_readlane_b32 s17, v252, 38
	global_load_dword v6, v[2:3], off
	v_lshl_add_u64 v[2:3], s[24:25], 0, v[0:1]
	v_readlane_b32 s14, v252, 32
	v_readlane_b32 s15, v252, 33
	global_load_dword v7, v[2:3], off
	v_writelane_b32 v251, s85, 4
	v_lshl_add_u64 v[2:3], s[14:15], 0, v[0:1]
	v_lshl_add_u64 v[0:1], s[16:17], 0, v[0:1]
	global_load_dword v2, v[2:3], off
	v_writelane_b32 v251, s75, 5
	global_load_dword v0, v[0:1], off
	v_mbcnt_lo_u32_b32 v1, -1, 0
	v_mbcnt_hi_u32_b32 v1, -1, v1
	v_and_b32_e32 v3, 64, v1
	v_xor_b32_e32 v8, 1, v1
	v_add_u32_e32 v3, 64, v3
	v_xor_b32_e32 v9, 2, v1
	v_cmp_lt_i32_e32 vcc, v8, v3
	v_xor_b32_e32 v10, 4, v1
	v_xor_b32_e32 v11, 8, v1
	v_cndmask_b32_e32 v8, v1, v8, vcc
	v_cmp_lt_i32_e32 vcc, v9, v3
	v_xor_b32_e32 v12, 16, v1
	v_xor_b32_e32 v13, 32, v1
	v_cndmask_b32_e32 v9, v1, v9, vcc
	v_cmp_lt_i32_e32 vcc, v10, v3
	v_writelane_b32 v251, s96, 6
	v_readlane_b32 s1, v252, 19
	v_cndmask_b32_e32 v10, v1, v10, vcc
	v_cmp_lt_i32_e32 vcc, v11, v3
	v_writelane_b32 v251, s97, 7
	v_writelane_b32 v251, s83, 8
	v_cndmask_b32_e32 v11, v1, v11, vcc
	v_cmp_lt_i32_e32 vcc, v12, v3
	v_writelane_b32 v251, s92, 9
	s_cselect_b64 s[0:1], -1, 0
	v_cndmask_b32_e32 v12, v1, v12, vcc
	v_cmp_lt_i32_e32 vcc, v13, v3
	v_lshlrev_b32_e32 v3, 2, v8
	v_lshlrev_b32_e32 v8, 2, v9
	v_cndmask_b32_e32 v1, v1, v13, vcc
	v_lshlrev_b32_e32 v9, 2, v10
	v_lshlrev_b32_e32 v10, 2, v11
	v_lshlrev_b32_e32 v11, 2, v12
	v_lshlrev_b32_e32 v12, 2, v1
	v_writelane_b32 v251, s93, 10
	v_writelane_b32 v251, s70, 11
	s_cmpk_gt_i32 s72, 0xff
	s_mov_b32 s85, 0
	v_writelane_b32 v251, s71, 12
	v_writelane_b32 v251, s82, 13
	v_writelane_b32 v251, s73, 14
	v_writelane_b32 v251, s0, 15
	v_readlane_b32 s26, v252, 47
	v_readlane_b32 s27, v252, 48
	v_writelane_b32 v251, s1, 16
	v_readlane_b32 s28, v252, 49
	v_readlane_b32 s29, v252, 50
	v_readlane_b32 s30, v252, 51
	v_readlane_b32 s31, v252, 52
	v_readlane_b32 s2, v252, 20
	v_readlane_b32 s3, v252, 21
	v_readlane_b32 s4, v252, 22
	v_readlane_b32 s5, v252, 23
	v_readlane_b32 s6, v252, 24
	v_readlane_b32 s7, v252, 25
	v_readlane_b32 s8, v252, 26
	v_readlane_b32 s9, v252, 27
	v_readlane_b32 s10, v252, 28
	v_readlane_b32 s11, v252, 29
	v_readlane_b32 s12, v252, 30
	v_readlane_b32 s13, v252, 31
	v_writelane_b32 v251, s72, 17
	s_waitcnt vmcnt(0)
	v_mul_f32_e32 v1, v4, v5
	ds_bpermute_b32 v1, v3, v1
	s_waitcnt lgkmcnt(0)
	v_fmac_f32_e32 v1, v4, v5
	ds_bpermute_b32 v5, v8, v1
	v_mul_f32_e32 v13, v6, v7
	ds_bpermute_b32 v13, v3, v13
	v_and_b32_e32 v14, 0x7fffffff, v2
	ds_bpermute_b32 v14, v3, v14
	v_and_b32_e32 v15, 0x7fffffff, v0
	ds_bpermute_b32 v3, v3, v15
	v_max_f32_e64 v2, |v2|, |v2|
	v_max_f32_e64 v0, |v0|, |v0|
	s_waitcnt lgkmcnt(1)
	v_max_f32_e32 v4, v14, v14
	v_max_f32_e32 v2, v2, v4
	s_waitcnt lgkmcnt(0)
	v_max_f32_e32 v3, v3, v3
	v_max_f32_e32 v0, v0, v3
	ds_bpermute_b32 v3, v8, v2
	ds_bpermute_b32 v4, v8, v0
	v_fmac_f32_e32 v13, v6, v7
	ds_bpermute_b32 v6, v8, v13
	v_add_f32_e32 v1, v1, v5
	s_waitcnt lgkmcnt(2)
	v_max_f32_e32 v3, v3, v3
	s_waitcnt lgkmcnt(1)
	v_max_f32_e32 v4, v4, v4
	v_max_f32_e32 v2, v2, v3
	v_max_f32_e32 v0, v0, v4
	ds_bpermute_b32 v3, v9, v2
	ds_bpermute_b32 v4, v9, v0
	s_waitcnt lgkmcnt(2)
	v_add_f32_e32 v5, v13, v6
	ds_bpermute_b32 v6, v9, v1
	ds_bpermute_b32 v7, v9, v5
	s_waitcnt lgkmcnt(3)
	v_max_f32_e32 v3, v3, v3
	s_waitcnt lgkmcnt(2)
	v_max_f32_e32 v4, v4, v4
	v_max_f32_e32 v2, v2, v3
	v_max_f32_e32 v0, v0, v4
	s_waitcnt lgkmcnt(1)
	v_add_f32_e32 v1, v1, v6
	ds_bpermute_b32 v3, v10, v2
	ds_bpermute_b32 v4, v10, v0
	s_waitcnt lgkmcnt(2)
	v_add_f32_e32 v5, v5, v7
	ds_bpermute_b32 v6, v10, v1
	ds_bpermute_b32 v7, v10, v5
	s_waitcnt lgkmcnt(3)
	v_max_f32_e32 v3, v3, v3
	s_waitcnt lgkmcnt(2)
	v_max_f32_e32 v4, v4, v4
	v_max_f32_e32 v2, v2, v3
	s_waitcnt lgkmcnt(1)
	v_add_f32_e32 v1, v1, v6
	v_max_f32_e32 v0, v0, v4
	s_waitcnt lgkmcnt(0)
	v_add_f32_e32 v5, v5, v7
	ds_bpermute_b32 v6, v11, v1
	ds_bpermute_b32 v3, v11, v2
	ds_bpermute_b32 v8, v11, v0
	ds_bpermute_b32 v7, v11, v5
	s_waitcnt lgkmcnt(3)
	v_add_f32_e32 v6, v1, v6
	s_waitcnt lgkmcnt(2)
	v_max_f32_e32 v1, v3, v3
	s_waitcnt lgkmcnt(1)
	v_max_f32_e32 v3, v8, v8
	s_waitcnt lgkmcnt(0)
	v_add_f32_e32 v4, v5, v7
	v_max_f32_e32 v1, v2, v1
	v_max_f32_e32 v0, v0, v3
	ds_bpermute_b32 v7, v12, v6
	ds_bpermute_b32 v5, v12, v4
	ds_bpermute_b32 v3, v12, v1
	ds_bpermute_b32 v2, v12, v0
	s_cbranch_scc1 .LBB0_449
; #define LAS __attribute__((address_space(3)))
; __device__ __forceinline__ int pi32(int i) { return (i & 0x13) | ((i & 8) >> 1) | ((i & 4) << 1); }
; __device__ __forceinline__ int lane_now() { int l; asm volatile("v_mbcnt_lo_u32_b32 %0, -1, 0\n\tv_mbcnt_hi_u32_b32 %0, -1, %0" : "=v"(l)); return l; }
; template <bool FIXM> __device__ __forceinline__ void diff_unit(int b, int h, int qb, float lam, const bf16* U, const bf16* VTa, bf16* Y, const float* subg, const float* qgain, const int* pos, unsigned char* lds, int tid, int wid, int lane) {
;     lane = lane_now(); tid = wid * 64 + lane;
;     const int r32 = lane & 31, hi = lane >> 5, prow = pi32(r32);
;     const int q0 = qb * 256, t0 = q0 + 32 * wid, tq = t0 + r32;
;     const size_t rowbase = (size_t)b * S;
;     const int NT = 4 * qb + 4, mylast = 4 * qb + (wid >> 1);
;     f32x16 o[4];
; #pragma unroll 1
;     for (int c = 0; c < 2; ++c) {
;         LAS unsigned char* qlds = (LAS unsigned char*)lds + 98304 + wid * 4096 + lane * 16;
; __global__ void __launch_bounds__(NWAVES * 64, 2) hybrid_fwd(Args args) {
;     ...
;         { const float p1 = args.in[9][lane4] * args.in[10][lane4], p2 = args.in[11][lane4] * args.in[12][lane4];
;           lam = expf(wave_sum(p1)) - expf(wave_sum(p2)) + 0.2f; }
;         bool fixm;
;         { float gq = fabsf(args.in[7][lane4]), gk = fabsf(args.in[8][lane4]);
; #pragma unroll
;           for (int o2 = 1; o2 < 64; o2 <<= 1) { gq = fmaxf(gq, __shfl_xor(gq, o2)); gk = fmaxf(gk, __shfl_xor(gk, o2)); }
;           fixm = (8.f * gq * gk * LOG2E <= 100.f); }
	s_waitcnt lgkmcnt(3)
	v_add_f32_e32 v6, v6, v7
	s_mov_b32 s0, 0x3fb8aa3b
	v_mul_f32_e32 v7, 0x3fb8aa3b, v6
	v_fma_f32 v8, v6, s0, -v7
	v_rndne_f32_e32 v9, v7
	v_fmac_f32_e32 v8, 0x32a5705f, v6
	v_sub_f32_e32 v7, v7, v9
	v_add_f32_e32 v7, v7, v8
	v_exp_f32_e32 v7, v7
	v_cvt_i32_f32_e32 v8, v9
	s_waitcnt lgkmcnt(2)
	v_add_f32_e32 v4, v4, v5
	s_waitcnt lgkmcnt(1)
	v_max_f32_e32 v3, v3, v3
	v_max_f32_e32 v1, v1, v1
	v_mul_f32_e32 v5, 0x3fb8aa3b, v4
	v_max_f32_e32 v1, v1, v3
	s_waitcnt lgkmcnt(0)
	v_max_f32_e32 v2, v2, v2
	v_max_f32_e32 v0, v0, v0
	v_ldexp_f32 v7, v7, v8
	s_mov_b32 s1, 0xc2ce8ed0
	v_fma_f32 v8, v4, s0, -v5
	v_rndne_f32_e32 v9, v5
	v_max_f32_e32 v0, v0, v2
	v_mul_f32_e32 v1, 0x41000000, v1
	v_cmp_ngt_f32_e32 vcc, s1, v6
	s_mov_b32 s2, 0x42b17218
	v_fmac_f32_e32 v8, 0x32a5705f, v4
	v_sub_f32_e32 v5, v5, v9
	v_mul_f32_e32 v0, v0, v1
	v_cndmask_b32_e32 v7, 0, v7, vcc
	v_add_f32_e32 v5, v5, v8
	v_cvt_i32_f32_e32 v8, v9
	v_mov_b32_e32 v9, 0x7f800000
	v_cmp_nlt_f32_e32 vcc, s2, v6
	v_mul_f32_e32 v0, 0x3fb8aa3b, v0
	s_mov_b32 s0, 0x42c80000
	v_cndmask_b32_e32 v6, v9, v7, vcc
	v_cmp_ngt_f32_e32 vcc, s1, v4
	v_cmp_ge_f32_e64 s[0:1], s0, v0
	v_exp_f32_e32 v5, v5
	s_mov_b64 s[88:89], 0x400000
	v_writelane_b32 v251, s0, 18
	v_mov_b32_e32 v1, 0
	v_ldexp_f32 v5, v5, v8
	v_writelane_b32 v251, s1, 19
	v_readlane_b32 s1, v252, 36
	s_lshl_b32 s0, s1, 5
	v_writelane_b32 v251, s0, 20
	v_cndmask_b32_e32 v5, 0, v5, vcc
	v_readlane_b32 s0, v251, 13
	v_cmp_nlt_f32_e32 vcc, s2, v4
	s_lshr_b32 s2, s0, 7
	s_lshl_b32 s0, s1, 12
	s_add_i32 s0, s0, 0
	s_add_i32 s0, s0, 0x18000
	v_writelane_b32 v251, s0, 21
	s_lshl_b32 s0, s1, 3
	v_writelane_b32 v251, s0, 22
	s_lshl_b32 s0, s1, 10
	s_add_i32 s67, s0, 0
	s_add_i32 s0, s67, 0x14000
	v_writelane_b32 v251, s0, 23
	s_add_i32 s0, s67, 0x16000
	v_writelane_b32 v251, s0, 24
	s_add_i32 s0, s67, 0x10000
	v_writelane_b32 v251, s0, 25
	s_add_i32 s0, s67, 0x12000
	v_writelane_b32 v251, s0, 26
	v_writelane_b32 v251, s2, 27
	s_sub_i32 s0, 0, s2
	v_writelane_b32 v251, s0, 28
	s_add_i32 s0, s67, 0x2000
	v_writelane_b32 v251, s0, 29
	s_add_i32 s0, s67, 0x8000
	v_cndmask_b32_e32 v4, v9, v5, vcc
	v_writelane_b32 v251, s0, 30
	s_add_i32 s0, s67, 0xa000
	v_sub_f32_e32 v4, v6, v4
	v_writelane_b32 v251, s0, 31
	v_add_f32_e32 v222, 0x3e4ccccd, v4
	s_movk_i32 s20, 0x1600
	s_mov_b32 s3, 0xc2fc0000
	v_mov_b32_e32 v223, 0x358637bd
	v_mov_b32_e32 v224, 0x260
	s_mov_b32 s66, 0x3e38aa3b
	s_mov_b64 s[86:87], 0x400
	s_add_i32 s94, s67, 0x4000
	s_add_i32 s95, s67, 0xc000
	s_add_i32 s70, s67, 0xe000
	s_add_i32 s71, s67, 0x6000
	v_mov_b32_e32 v225, 0x42800000
	v_not_b32_e32 v226, 63
	v_mov_b32_e32 v227, 0xff800000
	v_mov_b32_e32 v228, 0x58000
	v_readlane_b32 s1, v251, 17
	v_writelane_b32 v251, s76, 32
	s_nop 1
	v_writelane_b32 v251, s77, 33
	s_branch .LBB0_376

; #define LAS __attribute__((address_space(3)))
; __device__ __forceinline__ int pi32(int i) { return (i & 0x13) | ((i & 8) >> 1) | ((i & 4) << 1); }
; __device__ __forceinline__ void swa_unit(int b, int kvh, int qb, const bf16* U, const bf16* VTb, bf16* Y, const float* sinks, const float* qgain, const int* pos, unsigned char* lds, int wid, int lane) {
;     const int r32 = lane & 31, hi = lane >> 5, prow = pi32(r32);
;     const int q0 = qb * 256, t0 = q0 + 32 * wid, tq = t0 + r32;
;     const size_t rowbase = (size_t)b * S;
;     const int T0 = (q0 >= 128) ? (q0 - 128) >> 6 : 0, T1 = (q0 + 255) >> 6, nT = T1 - T0 + 1;
;     {
;         const int srow = 8 * wid + (lane >> 3), sch = (lane & 7) ^ ((srow >> 1) & 7);
;         const char* kb_u = (const char*)(U + (rowbase + 64 * T0) * EU + C_KB + kvh * 64);
;         const char* vb_u = (const char*)(VTb + ((size_t)(b * 128 + kvh * 64)) * S + 64 * T0);
;         const unsigned koff = (unsigned)(srow * EU + 8 * sch) * 2u, voff = (unsigned)(srow * S + 8 * sch) * 2u;
;         LAS unsigned char* ldsl = (LAS unsigned char*)lds + wid * 1024;
; #pragma unroll 1
;         for (int s = 0; s < nT; ++s) {
;             __builtin_amdgcn_global_load_lds((const unsigned*)(kb_u + (size_t)s * (64 * EU * 2) + koff), (LAS unsigned*)(ldsl + s * 8192), 16, 0, 0);
;             __builtin_amdgcn_global_load_lds((const unsigned*)(vb_u + (size_t)s * 128 + voff), (LAS unsigned*)(ldsl + 49152 + s * 8192), 16, 0, 0);
;         }
;         asm volatile("s_waitcnt vmcnt(0)" ::: "memory");
;         __syncthreads();
;     }
;     const LAS unsigned char* kfp = (const LAS unsigned char*)lds + prow * 128; const LAS unsigned char* vfp = (const LAS unsigned char*)lds + 49152 + r32 * 128;
;     unsigned kofs[4], vofs[4];
; #pragma unroll
;     for (int k4 = 0; k4 < 4; ++k4) { kofs[k4] = ((2 * k4 + hi) ^ ((prow >> 1) & 7)) * 16; vofs[k4] = ((2 * k4 + hi) ^ ((r32 >> 1) & 7)) * 16; }
; __global__ void __launch_bounds__(NWAVES * 64, 2) hybrid_fwd(Args args) {
;     ...
;         for (int u = vcu; u < 256; u += G) swa_unit(u >> 6, (u >> 5) & 1, u & 31, U, VTb, Y, args.in[16], args.in[14], pos, lds, wid, lane4b);
.LBB0_449:
	v_readlane_b32 s0, v251, 15
	v_readlane_b32 s1, v251, 16
	v_readlane_b32 s70, v251, 11
	v_readlane_b32 s92, v251, 9
	v_readlane_b32 s96, v251, 6
	v_readlane_b32 s68, v251, 2
	v_readlane_b32 s86, v252, 56
	v_readlane_b32 s88, v251, 0
	v_readlane_b32 s90, v252, 62
	v_readlane_b32 s78, v252, 60
	v_readlane_b32 s80, v252, 58
	s_andn2_b64 vcc, exec, s[0:1]
	v_readlane_b32 s73, v251, 14
	v_readlane_b32 s82, v251, 13
	v_readlane_b32 s71, v251, 12
	v_readlane_b32 s93, v251, 10
	v_readlane_b32 s83, v251, 8
	v_readlane_b32 s72, v251, 17
	v_readlane_b32 s97, v251, 7
	v_readlane_b32 s75, v251, 5
	v_readlane_b32 s85, v251, 4
	v_readlane_b32 s69, v251, 3
	v_readlane_b32 s87, v252, 57
	v_readlane_b32 s89, v251, 1
	v_readlane_b32 s91, v252, 63
	v_readlane_b32 s79, v252, 61
	v_readlane_b32 s81, v252, 59
	v_mbcnt_lo_u32_b32 v0, -1, 0
	v_mbcnt_hi_u32_b32 v0, -1, v0
	s_cbranch_vccnz .LBB0_464
	v_readlane_b32 s2, v252, 36
	s_waitcnt lgkmcnt(0)
	v_ashrrev_i32_e32 v7, 3, v0
	v_lshrrev_b32_e32 v2, 1, v0
	v_lshl_add_u32 v8, s2, 3, v7
	v_lshlrev_b32_e32 v3, 1, v0
	v_lshrrev_b32_e32 v8, 1, v8
	v_and_b32_e32 v4, 19, v0
	v_and_b32_e32 v5, 4, v2
	v_and_b32_e32 v6, 8, v3
	v_xor_b32_e32 v8, v8, v0
	v_and_b32_e32 v126, 31, v0
	v_ashrrev_i32_e32 v1, 5, v0
	v_or3_b32 v3, v5, v4, v6
	v_lshlrev_b32_e32 v8, 3, v8
	v_cmp_gt_u32_e32 vcc, 32, v0
	v_lshlrev_b32_e32 v0, 14, v7
	v_and_b32_e32 v8, 56, v8
	v_lshrrev_b32_e32 v3, 1, v3
	v_lshl_add_u32 v0, s2, 17, v0
	s_lshl_b32 s0, s2, 10
	v_bitop3_b32 v10, v3, v1, 7 bitop3:0x6c
	v_bitop3_b32 v11, v2, v1, 7 bitop3:0x6c
	v_add_u32_e32 v12, 2, v1
	v_add_u32_e32 v14, 4, v1
	v_add_u32_e32 v16, 6, v1
	v_lshlrev_b32_e32 v96, 3, v1
	v_lshlrev_b32_e32 v98, 2, v1
	v_lshl_or_b32 v0, v8, 1, v0
	v_mov_b32_e32 v1, 0
	s_add_i32 s16, s0, 0
	v_bitop3_b32 v13, v3, v12, 7 bitop3:0x6c
	v_bitop3_b32 v12, v12, v2, 7 bitop3:0x78
	v_bitop3_b32 v15, v3, v14, 7 bitop3:0x6c
	v_bitop3_b32 v14, v14, v2, 7 bitop3:0x78
	v_bitop3_b32 v17, v3, v16, 7 bitop3:0x6c
	v_bitop3_b32 v16, v16, v2, 7 bitop3:0x78
	v_lshl_add_u64 v[2:3], s[70:71], 0, v[0:1]
	s_mov_b64 s[0:1], 0x8000000
	v_lshl_add_u64 v[102:103], v[2:3], 0, s[0:1]
	s_movk_i32 s1, 0xb00
	s_mul_i32 s0, s2, 0x5800
	v_mul_lo_u32 v0, v7, s1
	v_add_u32_e32 v0, s0, v0
	v_or_b32_e32 v0, v0, v8
	s_lshl_b32 s11, s2, 5
	v_lshlrev_b32_e32 v0, 1, v0
	v_lshl_add_u64 v[2:3], s[70:71], 0, v[0:1]
	v_or_b32_e32 v0, s11, v126
	v_sub_u32_e32 v128, v0, v96
	v_or3_b32 v0, v4, v6, v5
	v_lshlrev_b32_e32 v9, 7, v126
	v_ashrrev_i32_e32 v97, 31, v96
	s_mov_b64 s[0:1], 0xa001000
	v_lshlrev_b32_e32 v0, 7, v0
	s_mov_b32 s3, 0
	v_cndmask_b32_e64 v127, 0, 1.0, vcc
	v_ashrrev_i32_e32 v99, 31, v98
	v_lshl_add_u64 v[100:101], v[96:97], 1, s[86:87]
	v_lshl_add_u64 v[104:105], v[2:3], 0, s[0:1]
	v_lshl_add_u32 v129, v16, 4, v9
	v_lshl_add_u32 v130, v14, 4, v9
	v_lshl_add_u32 v131, v12, 4, v9
	v_lshl_add_u32 v132, v11, 4, v9
	v_lshl_add_u32 v133, v17, 4, v0
	v_lshl_add_u32 v134, v15, 4, v0
	v_lshl_add_u32 v135, v13, 4, v0
	v_lshl_add_u32 v136, v10, 4, v0
	s_movk_i32 s17, 0x1600
	s_mov_b64 s[4:5], 0x80
	s_mov_b64 s[6:7], 0x58000
	v_mov_b64_e32 v[106:107], s[76:77]
	s_mov_b64 s[8:9], 0x1200
	s_mov_b32 s18, 0xc2fc0000
	v_mov_b32_e32 v137, 0x358637bd
	s_mov_b32 s19, 0xf800000
	v_mov_b32_e32 v138, 0x260
	s_mov_b32 s10, 0x3e38aa3b
	s_movk_i32 s20, 0x80
	s_movk_i32 s21, 0xff7f
	v_mov_b32_e32 v139, 0x42800000
	v_not_b32_e32 v140, 63
	v_mov_b32_e32 v141, 0xff800000
	s_mov_b32 s22, s72
	s_mov_b32 s23, s72
	s_branch .LBB0_452
